# EpiResid (W_o + down) epilogues hand-written: packed sums of squares, batched reductions (on top of the other hand-written epilogues)
# speedup vs baseline: 1.0175x; 1.0010x over previous
.LBB0_1022:
	s_lshl_b32 s0, s79, 8
	s_add_i32 s0, s0, s55
	v_and_or_b32 v140, v193, 15, s0
	v_bfe_u32 v141, v193, 4, 2
	s_lshl_b32 vcc_lo, s4, 9
	s_lshl_b32 vcc_hi, s71, 1
	s_or_b32 vcc_lo, vcc_lo, vcc_hi
	v_lshl_or_b32 v142, v141, 4, vcc_lo
	v_lshl_add_u32 v142, v140, 11, v142
	v_pk_mul_f32 v[174:175], v[114:115], v[114:115]
	v_pk_fma_f32 v[174:175], v[116:117], v[116:117], v[174:175]
	v_pk_fma_f32 v[174:175], v[118:119], v[118:119], v[174:175]
	v_pk_fma_f32 v[174:175], v[120:121], v[120:121], v[174:175]
	v_pk_fma_f32 v[174:175], v[122:123], v[122:123], v[174:175]
	v_pk_fma_f32 v[174:175], v[124:125], v[124:125], v[174:175]
	v_pk_fma_f32 v[174:175], v[126:127], v[126:127], v[174:175]
	v_pk_fma_f32 v[174:175], v[128:129], v[128:129], v[174:175]
	v_add_u32_e32 v143, 0x0, v142
	v_cvt_pk_bf16_f32 v114, v114, v115
	v_cvt_pk_bf16_f32 v115, v116, v117
	v_cvt_pk_bf16_f32 v116, v118, v119
	v_cvt_pk_bf16_f32 v117, v120, v121
	global_store_dwordx4 v143, v[114:117], s[2:3]
	v_cvt_pk_bf16_f32 v122, v122, v123
	v_cvt_pk_bf16_f32 v123, v124, v125
	v_cvt_pk_bf16_f32 v124, v126, v127
	v_cvt_pk_bf16_f32 v125, v128, v129
	global_store_dwordx4 v143, v[122:125], s[2:3] offset:256
	v_add_f32_e32 v150, v174, v175
	v_pk_mul_f32 v[176:177], v[98:99], v[98:99]
	v_pk_fma_f32 v[176:177], v[100:101], v[100:101], v[176:177]
	v_pk_fma_f32 v[176:177], v[102:103], v[102:103], v[176:177]
	v_pk_fma_f32 v[176:177], v[104:105], v[104:105], v[176:177]
	v_pk_fma_f32 v[176:177], v[106:107], v[106:107], v[176:177]
	v_pk_fma_f32 v[176:177], v[108:109], v[108:109], v[176:177]
	v_pk_fma_f32 v[176:177], v[110:111], v[110:111], v[176:177]
	v_pk_fma_f32 v[176:177], v[112:113], v[112:113], v[176:177]
	v_add_u32_e32 v146, 0x8000, v142
	v_cvt_pk_bf16_f32 v98, v98, v99
	v_cvt_pk_bf16_f32 v99, v100, v101
	v_cvt_pk_bf16_f32 v100, v102, v103
	v_cvt_pk_bf16_f32 v101, v104, v105
	global_store_dwordx4 v146, v[98:101], s[2:3]
	v_cvt_pk_bf16_f32 v106, v106, v107
	v_cvt_pk_bf16_f32 v107, v108, v109
	v_cvt_pk_bf16_f32 v108, v110, v111
	v_cvt_pk_bf16_f32 v109, v112, v113
	global_store_dwordx4 v146, v[106:109], s[2:3] offset:256
	v_add_f32_e32 v151, v176, v177
	v_pk_mul_f32 v[174:175], v[70:71], v[70:71]
	v_pk_fma_f32 v[174:175], v[72:73], v[72:73], v[174:175]
	v_pk_fma_f32 v[174:175], v[78:79], v[78:79], v[174:175]
	v_pk_fma_f32 v[174:175], v[80:81], v[80:81], v[174:175]
	v_pk_fma_f32 v[174:175], v[86:87], v[86:87], v[174:175]
	v_pk_fma_f32 v[174:175], v[88:89], v[88:89], v[174:175]
	v_pk_fma_f32 v[174:175], v[94:95], v[94:95], v[174:175]
	v_pk_fma_f32 v[174:175], v[96:97], v[96:97], v[174:175]
	v_add_u32_e32 v143, 0x10000, v142
	v_cvt_pk_bf16_f32 v70, v70, v71
	v_cvt_pk_bf16_f32 v71, v72, v73
	v_cvt_pk_bf16_f32 v72, v78, v79
	v_cvt_pk_bf16_f32 v73, v80, v81
	global_store_dwordx4 v143, v[70:73], s[2:3]
	v_cvt_pk_bf16_f32 v86, v86, v87
	v_cvt_pk_bf16_f32 v87, v88, v89
	v_cvt_pk_bf16_f32 v88, v94, v95
	v_cvt_pk_bf16_f32 v89, v96, v97
	global_store_dwordx4 v143, v[86:89], s[2:3] offset:256
	v_add_f32_e32 v152, v174, v175
	v_pk_mul_f32 v[176:177], v[34:35], v[34:35]
	v_pk_fma_f32 v[176:177], v[36:37], v[36:37], v[176:177]
	v_pk_fma_f32 v[176:177], v[46:47], v[46:47], v[176:177]
	v_pk_fma_f32 v[176:177], v[48:49], v[48:49], v[176:177]
	v_pk_fma_f32 v[176:177], v[58:59], v[58:59], v[176:177]
	v_pk_fma_f32 v[176:177], v[60:61], v[60:61], v[176:177]
	v_pk_fma_f32 v[176:177], v[66:67], v[66:67], v[176:177]
	v_pk_fma_f32 v[176:177], v[68:69], v[68:69], v[176:177]
	v_add_u32_e32 v146, 0x18000, v142
	v_cvt_pk_bf16_f32 v34, v34, v35
	v_cvt_pk_bf16_f32 v35, v36, v37
	v_cvt_pk_bf16_f32 v36, v46, v47
	v_cvt_pk_bf16_f32 v37, v48, v49
	global_store_dwordx4 v146, v[34:37], s[2:3]
	v_cvt_pk_bf16_f32 v58, v58, v59
	v_cvt_pk_bf16_f32 v59, v60, v61
	v_cvt_pk_bf16_f32 v60, v66, v67
	v_cvt_pk_bf16_f32 v61, v68, v69
	global_store_dwordx4 v146, v[58:61], s[2:3] offset:256
	v_add_f32_e32 v153, v176, v177
	v_pk_mul_f32 v[174:175], v[22:23], v[22:23]
	v_pk_fma_f32 v[174:175], v[24:25], v[24:25], v[174:175]
	v_pk_fma_f32 v[174:175], v[30:31], v[30:31], v[174:175]
	v_pk_fma_f32 v[174:175], v[32:33], v[32:33], v[174:175]
	v_pk_fma_f32 v[174:175], v[38:39], v[38:39], v[174:175]
	v_pk_fma_f32 v[174:175], v[40:41], v[40:41], v[174:175]
	v_pk_fma_f32 v[174:175], v[54:55], v[54:55], v[174:175]
	v_pk_fma_f32 v[174:175], v[56:57], v[56:57], v[174:175]
	v_add_u32_e32 v143, 0x40000, v142
	v_cvt_pk_bf16_f32 v22, v22, v23
	v_cvt_pk_bf16_f32 v23, v24, v25
	v_cvt_pk_bf16_f32 v24, v30, v31
	v_cvt_pk_bf16_f32 v25, v32, v33
	global_store_dwordx4 v143, v[22:25], s[2:3]
	v_cvt_pk_bf16_f32 v38, v38, v39
	v_cvt_pk_bf16_f32 v39, v40, v41
	v_cvt_pk_bf16_f32 v40, v54, v55
	v_cvt_pk_bf16_f32 v41, v56, v57
	global_store_dwordx4 v143, v[38:41], s[2:3] offset:256
	v_add_f32_e32 v154, v174, v175
	v_pk_mul_f32 v[176:177], v[2:3], v[2:3]
	v_pk_fma_f32 v[176:177], v[4:5], v[4:5], v[176:177]
	v_pk_fma_f32 v[176:177], v[74:75], v[74:75], v[176:177]
	v_pk_fma_f32 v[176:177], v[76:77], v[76:77], v[176:177]
	v_pk_fma_f32 v[176:177], v[82:83], v[82:83], v[176:177]
	v_pk_fma_f32 v[176:177], v[84:85], v[84:85], v[176:177]
	v_pk_fma_f32 v[176:177], v[90:91], v[90:91], v[176:177]
	v_pk_fma_f32 v[176:177], v[92:93], v[92:93], v[176:177]
	v_add_u32_e32 v146, 0x48000, v142
	v_cvt_pk_bf16_f32 v2, v2, v3
	v_cvt_pk_bf16_f32 v3, v4, v5
	v_cvt_pk_bf16_f32 v4, v74, v75
	v_cvt_pk_bf16_f32 v5, v76, v77
	global_store_dwordx4 v146, v[2:5], s[2:3]
	v_cvt_pk_bf16_f32 v82, v82, v83
	v_cvt_pk_bf16_f32 v83, v84, v85
	v_cvt_pk_bf16_f32 v84, v90, v91
	v_cvt_pk_bf16_f32 v85, v92, v93
	global_store_dwordx4 v146, v[82:85], s[2:3] offset:256
	v_add_f32_e32 v155, v176, v177
	v_pk_mul_f32 v[174:175], v[26:27], v[26:27]
	v_pk_fma_f32 v[174:175], v[28:29], v[28:29], v[174:175]
	v_pk_fma_f32 v[174:175], v[42:43], v[42:43], v[174:175]
	v_pk_fma_f32 v[174:175], v[44:45], v[44:45], v[174:175]
	v_pk_fma_f32 v[174:175], v[50:51], v[50:51], v[174:175]
	v_pk_fma_f32 v[174:175], v[52:53], v[52:53], v[174:175]
	v_pk_fma_f32 v[174:175], v[62:63], v[62:63], v[174:175]
	v_pk_fma_f32 v[174:175], v[64:65], v[64:65], v[174:175]
	v_add_u32_e32 v143, 0x50000, v142
	v_cvt_pk_bf16_f32 v26, v26, v27
	v_cvt_pk_bf16_f32 v27, v28, v29
	v_cvt_pk_bf16_f32 v28, v42, v43
	v_cvt_pk_bf16_f32 v29, v44, v45
	global_store_dwordx4 v143, v[26:29], s[2:3]
	v_cvt_pk_bf16_f32 v50, v50, v51
	v_cvt_pk_bf16_f32 v51, v52, v53
	v_cvt_pk_bf16_f32 v52, v62, v63
	v_cvt_pk_bf16_f32 v53, v64, v65
	global_store_dwordx4 v143, v[50:53], s[2:3] offset:256
	v_add_f32_e32 v156, v174, v175
	v_pk_mul_f32 v[176:177], v[6:7], v[6:7]
	v_pk_fma_f32 v[176:177], v[8:9], v[8:9], v[176:177]
	v_pk_fma_f32 v[176:177], v[10:11], v[10:11], v[176:177]
	v_pk_fma_f32 v[176:177], v[12:13], v[12:13], v[176:177]
	v_pk_fma_f32 v[176:177], v[14:15], v[14:15], v[176:177]
	v_pk_fma_f32 v[176:177], v[16:17], v[16:17], v[176:177]
	v_pk_fma_f32 v[176:177], v[18:19], v[18:19], v[176:177]
	v_pk_fma_f32 v[176:177], v[20:21], v[20:21], v[176:177]
	v_add_u32_e32 v146, 0x58000, v142
	v_cvt_pk_bf16_f32 v6, v6, v7
	v_cvt_pk_bf16_f32 v7, v8, v9
	v_cvt_pk_bf16_f32 v8, v10, v11
	v_cvt_pk_bf16_f32 v9, v12, v13
	global_store_dwordx4 v146, v[6:9], s[2:3]
	v_cvt_pk_bf16_f32 v14, v14, v15
	v_cvt_pk_bf16_f32 v15, v16, v17
	v_cvt_pk_bf16_f32 v16, v18, v19
	v_cvt_pk_bf16_f32 v17, v20, v21
	global_store_dwordx4 v146, v[14:17], s[2:3] offset:256
	v_add_f32_e32 v157, v176, v177
	ds_swizzle_b32 v158, v150 offset:swizzle(SWAP,16)
	ds_swizzle_b32 v159, v151 offset:swizzle(SWAP,16)
	ds_swizzle_b32 v160, v152 offset:swizzle(SWAP,16)
	ds_swizzle_b32 v161, v153 offset:swizzle(SWAP,16)
	ds_swizzle_b32 v162, v154 offset:swizzle(SWAP,16)
	ds_swizzle_b32 v163, v155 offset:swizzle(SWAP,16)
	ds_swizzle_b32 v164, v156 offset:swizzle(SWAP,16)
	ds_swizzle_b32 v165, v157 offset:swizzle(SWAP,16)
	s_lshl_b32 s0, s4, 4
	s_lshl_b32 vcc_lo, s51, 2
	s_or_b32 s0, s0, vcc_lo
	v_mov_b32_e32 v147, s0
	v_lshl_add_u32 v147, v140, 6, v147
	v_add_u32_e32 v148, 0x2000, v147
	s_waitcnt lgkmcnt(0)
	v_add_f32_e32 v150, v150, v158
	v_add_f32_e32 v151, v151, v159
	v_add_f32_e32 v152, v152, v160
	v_add_f32_e32 v153, v153, v161
	v_add_f32_e32 v154, v154, v162
	v_add_f32_e32 v155, v155, v163
	v_add_f32_e32 v156, v156, v164
	v_add_f32_e32 v157, v157, v165
	v_mov_b32_e32 v166, v150
	v_mov_b32_e32 v167, v151
	v_mov_b32_e32 v168, v152
	v_mov_b32_e32 v169, v153
	v_mov_b32_e32 v170, v154
	v_mov_b32_e32 v171, v155
	v_mov_b32_e32 v172, v156
	v_mov_b32_e32 v173, v157
	v_permlane32_swap_b32_e32 v150, v166
	v_permlane32_swap_b32_e32 v151, v167
	v_permlane32_swap_b32_e32 v152, v168
	v_permlane32_swap_b32_e32 v153, v169
	v_permlane32_swap_b32_e32 v154, v170
	v_permlane32_swap_b32_e32 v155, v171
	v_permlane32_swap_b32_e32 v156, v172
	v_permlane32_swap_b32_e32 v157, v173
	v_add_f32_e32 v150, v150, v166
	v_add_f32_e32 v151, v151, v167
	v_add_f32_e32 v152, v152, v168
	v_add_f32_e32 v153, v153, v169
	v_add_f32_e32 v154, v154, v170
	v_add_f32_e32 v155, v155, v171
	v_add_f32_e32 v156, v156, v172
	v_add_f32_e32 v157, v157, v173
	s_mov_b64 exec, 0xffff
	global_store_dword v147, v150, s[8:9]
	global_store_dword v147, v151, s[8:9] offset:1024
	global_store_dword v147, v152, s[8:9] offset:2048
	global_store_dword v147, v153, s[8:9] offset:3072
	global_store_dword v148, v154, s[8:9]
	global_store_dword v148, v155, s[8:9] offset:1024
	global_store_dword v148, v156, s[8:9] offset:2048
	global_store_dword v148, v157, s[8:9] offset:3072
	s_mov_b64 exec, -1
	s_andn2_b64 vcc, exec, s[38:39]
	s_mov_b64 s[24:25], -1
	s_cbranch_vccnz .LBB0_1011
	v_mov_b32_e32 v3, v193
	s_lshl_b32 s0, s14, 8
	s_add_i32 s0, s0, s55
	v_and_or_b32 v2, v3, 15, s0
	s_lshl_b32 s0, s12, 8
	v_lshrrev_b32_e32 v3, 1, v3
	v_and_or_b32 v3, v3, 24, s0
	v_or_b32_e32 v4, s71, v3
	v_ashrrev_i32_e32 v3, 31, v2
	v_ashrrev_i32_e32 v5, 31, v4
	v_lshlrev_b64 v[6:7], 11, v[2:3]
	v_lshl_add_u64 v[6:7], s[2:3], 0, v[6:7]
	v_lshlrev_b64 v[4:5], 1, v[4:5]
	v_lshl_add_u64 v[10:11], v[6:7], 0, v[4:5]
	v_or_b32_e32 v6, 16, v2
	v_ashrrev_i32_e32 v7, 31, v6
	v_lshlrev_b64 v[6:7], 11, v[6:7]
	v_lshl_add_u64 v[6:7], s[2:3], 0, v[6:7]
	v_lshl_add_u64 v[6:7], v[6:7], 0, v[4:5]
	flat_load_dwordx4 v[62:65], v[10:11]
	flat_load_dwordx4 v[54:57], v[10:11] offset:256
	flat_load_dwordx4 v[58:61], v[6:7]
	flat_load_dwordx4 v[46:49], v[6:7] offset:256
	v_or_b32_e32 v6, 32, v2
	v_or_b32_e32 v2, 48, v2
	v_ashrrev_i32_e32 v7, 31, v6
	v_ashrrev_i32_e32 v3, 31, v2
	v_lshlrev_b64 v[6:7], 11, v[6:7]
	v_lshlrev_b64 v[2:3], 11, v[2:3]
	v_lshl_add_u64 v[6:7], s[2:3], 0, v[6:7]
	v_lshl_add_u64 v[2:3], s[2:3], 0, v[2:3]
	s_mov_b32 s0, 0x40000
	v_lshl_add_u64 v[6:7], v[6:7], 0, v[4:5]
	v_lshl_add_u64 v[2:3], v[2:3], 0, v[4:5]
	v_add_co_u32_e32 v4, vcc, s0, v10
	s_mov_b32 s0, 0x48000
	s_nop 0
	v_addc_co_u32_e32 v5, vcc, 0, v11, vcc
	s_mov_b64 s[24:25], 0x40000
	v_add_co_u32_e32 v8, vcc, s0, v10
	flat_load_dwordx4 v[50:53], v[6:7]
	flat_load_dwordx4 v[34:37], v[6:7] offset:256
	flat_load_dwordx4 v[38:41], v[2:3]
	flat_load_dwordx4 v[22:25], v[2:3] offset:256
	v_lshl_add_u64 v[2:3], v[10:11], 0, s[24:25]
	s_mov_b64 s[24:25], 0x48000
	v_addc_co_u32_e32 v9, vcc, 0, v11, vcc
	flat_load_dwordx4 v[30:33], v[4:5]
	s_nop 0
	flat_load_dwordx4 v[2:5], v[2:3] offset:256
	v_lshl_add_u64 v[6:7], v[10:11], 0, s[24:25]
	flat_load_dwordx4 v[26:29], v[8:9]
	flat_load_dwordx4 v[14:17], v[6:7] offset:256
	s_mov_b64 s[24:25], 0x50000
	v_add_co_u32_e32 v8, vcc, 0x50000, v10
	v_lshl_add_u64 v[6:7], v[10:11], 0, s[24:25]
	s_nop 0
	v_addc_co_u32_e32 v9, vcc, 0, v11, vcc
	s_mov_b64 s[24:25], 0x58000
	v_lshl_add_u64 v[18:19], v[10:11], 0, s[24:25]
	v_add_co_u32_e32 v10, vcc, 0x58000, v10
	flat_load_dwordx4 v[42:45], v[8:9]
	s_nop 0
	flat_load_dwordx4 v[6:9], v[6:7] offset:256
	v_addc_co_u32_e32 v11, vcc, 0, v11, vcc
	flat_load_dwordx4 v[10:13], v[10:11]
	s_nop 0
	flat_load_dwordx4 v[18:21], v[18:19] offset:256
	s_andn2_b64 vcc, exec, s[6:7]
	s_cbranch_vccnz .LBB0_1010
	s_barrier
	s_branch .LBB0_1010

.LBB0_1312:
	s_lshl_b32 s0, s77, 8
	s_add_i32 s0, s0, s44
	v_and_or_b32 v140, v193, 15, s0
	v_bfe_u32 v141, v193, 4, 2
	s_lshl_b32 vcc_lo, s4, 9
	s_lshl_b32 vcc_hi, s45, 1
	s_or_b32 vcc_lo, vcc_lo, vcc_hi
	v_lshl_or_b32 v142, v141, 4, vcc_lo
	v_lshl_add_u32 v142, v140, 11, v142
	v_pk_mul_f32 v[174:175], v[114:115], v[114:115]
	v_pk_fma_f32 v[174:175], v[116:117], v[116:117], v[174:175]
	v_pk_fma_f32 v[174:175], v[118:119], v[118:119], v[174:175]
	v_pk_fma_f32 v[174:175], v[120:121], v[120:121], v[174:175]
	v_pk_fma_f32 v[174:175], v[122:123], v[122:123], v[174:175]
	v_pk_fma_f32 v[174:175], v[124:125], v[124:125], v[174:175]
	v_pk_fma_f32 v[174:175], v[126:127], v[126:127], v[174:175]
	v_pk_fma_f32 v[174:175], v[128:129], v[128:129], v[174:175]
	v_add_u32_e32 v143, 0x0, v142
	v_cvt_pk_bf16_f32 v114, v114, v115
	v_cvt_pk_bf16_f32 v115, v116, v117
	v_cvt_pk_bf16_f32 v116, v118, v119
	v_cvt_pk_bf16_f32 v117, v120, v121
	global_store_dwordx4 v143, v[114:117], s[2:3]
	v_cvt_pk_bf16_f32 v122, v122, v123
	v_cvt_pk_bf16_f32 v123, v124, v125
	v_cvt_pk_bf16_f32 v124, v126, v127
	v_cvt_pk_bf16_f32 v125, v128, v129
	global_store_dwordx4 v143, v[122:125], s[2:3] offset:256
	v_add_f32_e32 v150, v174, v175
	v_pk_mul_f32 v[176:177], v[98:99], v[98:99]
	v_pk_fma_f32 v[176:177], v[100:101], v[100:101], v[176:177]
	v_pk_fma_f32 v[176:177], v[102:103], v[102:103], v[176:177]
	v_pk_fma_f32 v[176:177], v[104:105], v[104:105], v[176:177]
	v_pk_fma_f32 v[176:177], v[106:107], v[106:107], v[176:177]
	v_pk_fma_f32 v[176:177], v[108:109], v[108:109], v[176:177]
	v_pk_fma_f32 v[176:177], v[110:111], v[110:111], v[176:177]
	v_pk_fma_f32 v[176:177], v[112:113], v[112:113], v[176:177]
	v_add_u32_e32 v146, 0x8000, v142
	v_cvt_pk_bf16_f32 v98, v98, v99
	v_cvt_pk_bf16_f32 v99, v100, v101
	v_cvt_pk_bf16_f32 v100, v102, v103
	v_cvt_pk_bf16_f32 v101, v104, v105
	global_store_dwordx4 v146, v[98:101], s[2:3]
	v_cvt_pk_bf16_f32 v106, v106, v107
	v_cvt_pk_bf16_f32 v107, v108, v109
	v_cvt_pk_bf16_f32 v108, v110, v111
	v_cvt_pk_bf16_f32 v109, v112, v113
	global_store_dwordx4 v146, v[106:109], s[2:3] offset:256
	v_add_f32_e32 v151, v176, v177
	v_pk_mul_f32 v[174:175], v[70:71], v[70:71]
	v_pk_fma_f32 v[174:175], v[72:73], v[72:73], v[174:175]
	v_pk_fma_f32 v[174:175], v[78:79], v[78:79], v[174:175]
	v_pk_fma_f32 v[174:175], v[80:81], v[80:81], v[174:175]
	v_pk_fma_f32 v[174:175], v[86:87], v[86:87], v[174:175]
	v_pk_fma_f32 v[174:175], v[88:89], v[88:89], v[174:175]
	v_pk_fma_f32 v[174:175], v[94:95], v[94:95], v[174:175]
	v_pk_fma_f32 v[174:175], v[96:97], v[96:97], v[174:175]
	v_add_u32_e32 v143, 0x10000, v142
	v_cvt_pk_bf16_f32 v70, v70, v71
	v_cvt_pk_bf16_f32 v71, v72, v73
	v_cvt_pk_bf16_f32 v72, v78, v79
	v_cvt_pk_bf16_f32 v73, v80, v81
	global_store_dwordx4 v143, v[70:73], s[2:3]
	v_cvt_pk_bf16_f32 v86, v86, v87
	v_cvt_pk_bf16_f32 v87, v88, v89
	v_cvt_pk_bf16_f32 v88, v94, v95
	v_cvt_pk_bf16_f32 v89, v96, v97
	global_store_dwordx4 v143, v[86:89], s[2:3] offset:256
	v_add_f32_e32 v152, v174, v175
	v_pk_mul_f32 v[176:177], v[34:35], v[34:35]
	v_pk_fma_f32 v[176:177], v[36:37], v[36:37], v[176:177]
	v_pk_fma_f32 v[176:177], v[46:47], v[46:47], v[176:177]
	v_pk_fma_f32 v[176:177], v[48:49], v[48:49], v[176:177]
	v_pk_fma_f32 v[176:177], v[58:59], v[58:59], v[176:177]
	v_pk_fma_f32 v[176:177], v[60:61], v[60:61], v[176:177]
	v_pk_fma_f32 v[176:177], v[66:67], v[66:67], v[176:177]
	v_pk_fma_f32 v[176:177], v[68:69], v[68:69], v[176:177]
	v_add_u32_e32 v146, 0x18000, v142
	v_cvt_pk_bf16_f32 v34, v34, v35
	v_cvt_pk_bf16_f32 v35, v36, v37
	v_cvt_pk_bf16_f32 v36, v46, v47
	v_cvt_pk_bf16_f32 v37, v48, v49
	global_store_dwordx4 v146, v[34:37], s[2:3]
	v_cvt_pk_bf16_f32 v58, v58, v59
	v_cvt_pk_bf16_f32 v59, v60, v61
	v_cvt_pk_bf16_f32 v60, v66, v67
	v_cvt_pk_bf16_f32 v61, v68, v69
	global_store_dwordx4 v146, v[58:61], s[2:3] offset:256
	v_add_f32_e32 v153, v176, v177
	v_pk_mul_f32 v[174:175], v[22:23], v[22:23]
	v_pk_fma_f32 v[174:175], v[24:25], v[24:25], v[174:175]
	v_pk_fma_f32 v[174:175], v[30:31], v[30:31], v[174:175]
	v_pk_fma_f32 v[174:175], v[32:33], v[32:33], v[174:175]
	v_pk_fma_f32 v[174:175], v[38:39], v[38:39], v[174:175]
	v_pk_fma_f32 v[174:175], v[40:41], v[40:41], v[174:175]
	v_pk_fma_f32 v[174:175], v[54:55], v[54:55], v[174:175]
	v_pk_fma_f32 v[174:175], v[56:57], v[56:57], v[174:175]
	v_add_u32_e32 v143, 0x40000, v142
	v_cvt_pk_bf16_f32 v22, v22, v23
	v_cvt_pk_bf16_f32 v23, v24, v25
	v_cvt_pk_bf16_f32 v24, v30, v31
	v_cvt_pk_bf16_f32 v25, v32, v33
	global_store_dwordx4 v143, v[22:25], s[2:3]
	v_cvt_pk_bf16_f32 v38, v38, v39
	v_cvt_pk_bf16_f32 v39, v40, v41
	v_cvt_pk_bf16_f32 v40, v54, v55
	v_cvt_pk_bf16_f32 v41, v56, v57
	global_store_dwordx4 v143, v[38:41], s[2:3] offset:256
	v_add_f32_e32 v154, v174, v175
	v_pk_mul_f32 v[176:177], v[2:3], v[2:3]
	v_pk_fma_f32 v[176:177], v[4:5], v[4:5], v[176:177]
	v_pk_fma_f32 v[176:177], v[74:75], v[74:75], v[176:177]
	v_pk_fma_f32 v[176:177], v[76:77], v[76:77], v[176:177]
	v_pk_fma_f32 v[176:177], v[82:83], v[82:83], v[176:177]
	v_pk_fma_f32 v[176:177], v[84:85], v[84:85], v[176:177]
	v_pk_fma_f32 v[176:177], v[90:91], v[90:91], v[176:177]
	v_pk_fma_f32 v[176:177], v[92:93], v[92:93], v[176:177]
	v_add_u32_e32 v146, 0x48000, v142
	v_cvt_pk_bf16_f32 v2, v2, v3
	v_cvt_pk_bf16_f32 v3, v4, v5
	v_cvt_pk_bf16_f32 v4, v74, v75
	v_cvt_pk_bf16_f32 v5, v76, v77
	global_store_dwordx4 v146, v[2:5], s[2:3]
	v_cvt_pk_bf16_f32 v82, v82, v83
	v_cvt_pk_bf16_f32 v83, v84, v85
	v_cvt_pk_bf16_f32 v84, v90, v91
	v_cvt_pk_bf16_f32 v85, v92, v93
	global_store_dwordx4 v146, v[82:85], s[2:3] offset:256
	v_add_f32_e32 v155, v176, v177
	v_pk_mul_f32 v[174:175], v[26:27], v[26:27]
	v_pk_fma_f32 v[174:175], v[28:29], v[28:29], v[174:175]
	v_pk_fma_f32 v[174:175], v[42:43], v[42:43], v[174:175]
	v_pk_fma_f32 v[174:175], v[44:45], v[44:45], v[174:175]
	v_pk_fma_f32 v[174:175], v[50:51], v[50:51], v[174:175]
	v_pk_fma_f32 v[174:175], v[52:53], v[52:53], v[174:175]
	v_pk_fma_f32 v[174:175], v[62:63], v[62:63], v[174:175]
	v_pk_fma_f32 v[174:175], v[64:65], v[64:65], v[174:175]
	v_add_u32_e32 v143, 0x50000, v142
	v_cvt_pk_bf16_f32 v26, v26, v27
	v_cvt_pk_bf16_f32 v27, v28, v29
	v_cvt_pk_bf16_f32 v28, v42, v43
	v_cvt_pk_bf16_f32 v29, v44, v45
	global_store_dwordx4 v143, v[26:29], s[2:3]
	v_cvt_pk_bf16_f32 v50, v50, v51
	v_cvt_pk_bf16_f32 v51, v52, v53
	v_cvt_pk_bf16_f32 v52, v62, v63
	v_cvt_pk_bf16_f32 v53, v64, v65
	global_store_dwordx4 v143, v[50:53], s[2:3] offset:256
	v_add_f32_e32 v156, v174, v175
	v_pk_mul_f32 v[176:177], v[6:7], v[6:7]
	v_pk_fma_f32 v[176:177], v[8:9], v[8:9], v[176:177]
	v_pk_fma_f32 v[176:177], v[10:11], v[10:11], v[176:177]
	v_pk_fma_f32 v[176:177], v[12:13], v[12:13], v[176:177]
	v_pk_fma_f32 v[176:177], v[14:15], v[14:15], v[176:177]
	v_pk_fma_f32 v[176:177], v[16:17], v[16:17], v[176:177]
	v_pk_fma_f32 v[176:177], v[18:19], v[18:19], v[176:177]
	v_pk_fma_f32 v[176:177], v[20:21], v[20:21], v[176:177]
	v_add_u32_e32 v146, 0x58000, v142
	v_cvt_pk_bf16_f32 v6, v6, v7
	v_cvt_pk_bf16_f32 v7, v8, v9
	v_cvt_pk_bf16_f32 v8, v10, v11
	v_cvt_pk_bf16_f32 v9, v12, v13
	global_store_dwordx4 v146, v[6:9], s[2:3]
	v_cvt_pk_bf16_f32 v14, v14, v15
	v_cvt_pk_bf16_f32 v15, v16, v17
	v_cvt_pk_bf16_f32 v16, v18, v19
	v_cvt_pk_bf16_f32 v17, v20, v21
	global_store_dwordx4 v146, v[14:17], s[2:3] offset:256
	v_add_f32_e32 v157, v176, v177
	ds_swizzle_b32 v158, v150 offset:swizzle(SWAP,16)
	ds_swizzle_b32 v159, v151 offset:swizzle(SWAP,16)
	ds_swizzle_b32 v160, v152 offset:swizzle(SWAP,16)
	ds_swizzle_b32 v161, v153 offset:swizzle(SWAP,16)
	ds_swizzle_b32 v162, v154 offset:swizzle(SWAP,16)
	ds_swizzle_b32 v163, v155 offset:swizzle(SWAP,16)
	ds_swizzle_b32 v164, v156 offset:swizzle(SWAP,16)
	ds_swizzle_b32 v165, v157 offset:swizzle(SWAP,16)
	s_lshl_b32 s0, s4, 4
	s_lshl_b32 vcc_lo, s42, 2
	s_or_b32 s0, s0, vcc_lo
	v_mov_b32_e32 v147, s0
	v_lshl_add_u32 v147, v140, 6, v147
	v_add_u32_e32 v148, 0x2000, v147
	s_waitcnt lgkmcnt(0)
	v_add_f32_e32 v150, v150, v158
	v_add_f32_e32 v151, v151, v159
	v_add_f32_e32 v152, v152, v160
	v_add_f32_e32 v153, v153, v161
	v_add_f32_e32 v154, v154, v162
	v_add_f32_e32 v155, v155, v163
	v_add_f32_e32 v156, v156, v164
	v_add_f32_e32 v157, v157, v165
	v_mov_b32_e32 v166, v150
	v_mov_b32_e32 v167, v151
	v_mov_b32_e32 v168, v152
	v_mov_b32_e32 v169, v153
	v_mov_b32_e32 v170, v154
	v_mov_b32_e32 v171, v155
	v_mov_b32_e32 v172, v156
	v_mov_b32_e32 v173, v157
	v_permlane32_swap_b32_e32 v150, v166
	v_permlane32_swap_b32_e32 v151, v167
	v_permlane32_swap_b32_e32 v152, v168
	v_permlane32_swap_b32_e32 v153, v169
	v_permlane32_swap_b32_e32 v154, v170
	v_permlane32_swap_b32_e32 v155, v171
	v_permlane32_swap_b32_e32 v156, v172
	v_permlane32_swap_b32_e32 v157, v173
	v_add_f32_e32 v150, v150, v166
	v_add_f32_e32 v151, v151, v167
	v_add_f32_e32 v152, v152, v168
	v_add_f32_e32 v153, v153, v169
	v_add_f32_e32 v154, v154, v170
	v_add_f32_e32 v155, v155, v171
	v_add_f32_e32 v156, v156, v172
	v_add_f32_e32 v157, v157, v173
	s_mov_b64 exec, 0xffff
	global_store_dword v147, v150, s[8:9]
	global_store_dword v147, v151, s[8:9] offset:1024
	global_store_dword v147, v152, s[8:9] offset:2048
	global_store_dword v147, v153, s[8:9] offset:3072
	global_store_dword v148, v154, s[8:9]
	global_store_dword v148, v155, s[8:9] offset:1024
	global_store_dword v148, v156, s[8:9] offset:2048
	global_store_dword v148, v157, s[8:9] offset:3072
	s_mov_b64 exec, -1
	s_and_b64 vcc, exec, s[36:37]
	s_mov_b64 s[16:17], -1
	s_cbranch_vccnz .LBB0_1297
	v_mov_b32_e32 v3, v193
	s_lshl_b32 s0, s76, 8
	s_add_i32 s0, s0, s44
	v_and_or_b32 v2, v3, 15, s0
	s_lshl_b32 s0, s75, 8
	v_lshrrev_b32_e32 v3, 1, v3
	v_and_or_b32 v3, v3, 24, s0
	v_or_b32_e32 v4, s45, v3
	v_ashrrev_i32_e32 v3, 31, v2
	v_ashrrev_i32_e32 v5, 31, v4
	v_lshlrev_b64 v[6:7], 11, v[2:3]
	v_lshl_add_u64 v[6:7], s[2:3], 0, v[6:7]
	v_lshlrev_b64 v[4:5], 1, v[4:5]
	v_lshl_add_u64 v[10:11], v[6:7], 0, v[4:5]
	v_or_b32_e32 v6, 16, v2
	v_ashrrev_i32_e32 v7, 31, v6
	v_lshlrev_b64 v[6:7], 11, v[6:7]
	v_lshl_add_u64 v[6:7], s[2:3], 0, v[6:7]
	v_lshl_add_u64 v[6:7], v[6:7], 0, v[4:5]
	flat_load_dwordx4 v[62:65], v[10:11]
	flat_load_dwordx4 v[54:57], v[10:11] offset:256
	flat_load_dwordx4 v[58:61], v[6:7]
	flat_load_dwordx4 v[46:49], v[6:7] offset:256
	v_or_b32_e32 v6, 32, v2
	v_or_b32_e32 v2, 48, v2
	v_ashrrev_i32_e32 v7, 31, v6
	v_ashrrev_i32_e32 v3, 31, v2
	v_lshlrev_b64 v[6:7], 11, v[6:7]
	v_lshlrev_b64 v[2:3], 11, v[2:3]
	v_lshl_add_u64 v[6:7], s[2:3], 0, v[6:7]
	v_lshl_add_u64 v[2:3], s[2:3], 0, v[2:3]
	s_mov_b32 s0, 0x40000
	v_lshl_add_u64 v[6:7], v[6:7], 0, v[4:5]
	v_lshl_add_u64 v[2:3], v[2:3], 0, v[4:5]
	v_add_co_u32_e32 v4, vcc, s0, v10
	s_mov_b32 s0, 0x48000
	s_nop 0
	v_addc_co_u32_e32 v5, vcc, 0, v11, vcc
	s_mov_b64 s[16:17], 0x40000
	v_add_co_u32_e32 v8, vcc, s0, v10
	flat_load_dwordx4 v[50:53], v[6:7]
	flat_load_dwordx4 v[34:37], v[6:7] offset:256
	flat_load_dwordx4 v[38:41], v[2:3]
	flat_load_dwordx4 v[22:25], v[2:3] offset:256
	v_lshl_add_u64 v[2:3], v[10:11], 0, s[16:17]
	s_mov_b64 s[16:17], 0x48000
	v_addc_co_u32_e32 v9, vcc, 0, v11, vcc
	flat_load_dwordx4 v[30:33], v[4:5]
	s_nop 0
	flat_load_dwordx4 v[2:5], v[2:3] offset:256
	v_lshl_add_u64 v[6:7], v[10:11], 0, s[16:17]
	flat_load_dwordx4 v[26:29], v[8:9]
	flat_load_dwordx4 v[14:17], v[6:7] offset:256
	s_mov_b64 s[16:17], 0x50000
	v_add_co_u32_e32 v8, vcc, 0x50000, v10
	v_lshl_add_u64 v[6:7], v[10:11], 0, s[16:17]
	s_nop 0
	v_addc_co_u32_e32 v9, vcc, 0, v11, vcc
	s_mov_b64 s[16:17], 0x58000
	v_lshl_add_u64 v[18:19], v[10:11], 0, s[16:17]
	v_add_co_u32_e32 v10, vcc, 0x58000, v10
	flat_load_dwordx4 v[42:45], v[8:9]
	s_nop 0
	flat_load_dwordx4 v[6:9], v[6:7] offset:256
	v_addc_co_u32_e32 v11, vcc, 0, v11, vcc
	flat_load_dwordx4 v[10:13], v[10:11]
	s_nop 0
	flat_load_dwordx4 v[18:21], v[18:19] offset:256
	s_andn2_b64 vcc, exec, s[6:7]
	s_cbranch_vccnz .LBB0_1296
	s_barrier
	s_branch .LBB0_1296
